# phase A weight conversion (input-proj and gate/up, norm weight folded): 8 row loads + scales of a tile issued together instead of 8 dependent load-wait-multiply blocks
# speedup vs baseline: 1.0447x; 1.0089x over previous
; #define LAS __attribute__((address_space(3)))
; template <int MAP> __device__ __forceinline__ void prep_w(const float* __restrict__ W, int K, int ldw, bf16_t* __restrict__ Bt, int Np, int ldb, LAS unsigned char* lds, int tid, int bx, int G, const float* kscale = nullptr) {
;     const int ntp = Np >> 6, ntiles = ntp * (K >> 6), w = tid >> 6, lane = tid & 63;
;     float v[8];
;     int tile = bx;
;     if (tile < ntiles) { const int tk = tile / ntp, tp = tile - tk * ntp; const int col = mapcol<MAP>(tp * 64 + lane); const float* s = W + (size_t)(tk * 64 + 8 * w) * ldw + (col < 0 ? 0 : col);
; #pragma unroll
;         for (int i = 0; i < 8; ++i) v[i] = col >= 0 ? s[(size_t)i * ldw] * (kscale ? kscale[tk * 64 + 8 * w + i] : 1.0f) : 0.f; }
.LBB0_15:
	s_lshl_b32 s4, s6, 6
	v_lshl_add_u32 v8, v22, 3, s4
	v_mov_b64_e32 v[2:3], s[16:17]
	v_mad_i64_i32 v[2:3], s[4:5], v8, s61, v[2:3]
	s_cmp_lg_u64 s[14:15], 0
	s_cselect_b64 s[4:5], -1, 0
	v_max_i32_e32 v80, 0, v1
	v_cmp_lt_i32_e64 s[6:7], -1, v1
	v_cndmask_b32_e64 v1, 0, 1, s[4:5]
	v_ashrrev_i32_e32 v9, 31, v8
	v_lshl_add_u64 v[10:11], v[80:81], 2, v[2:3]
	v_mov_b32_e32 v0, 0
	v_cmp_ne_u32_e64 s[4:5], 1, v1
	v_mov_b32_e32 v1, 0
	v_mov_b32_e32 v2, 0
	v_mov_b32_e32 v3, 0
	v_mov_b32_e32 v4, 0
	v_mov_b32_e32 v5, 0
	v_mov_b32_e32 v6, 0
	v_mov_b32_e32 v7, 0
	s_and_b64 vcc, exec, s[4:5]
	s_cbranch_vccnz .Lks1_inp
	v_lshl_add_u64 v[88:89], v[8:9], 2, s[14:15]
	global_load_dwordx4 v[90:93], v[88:89], off
	global_load_dwordx4 v[94:97], v[88:89], off offset:16
	s_branch .Lks2_inp
.Lks1_inp:
	v_mov_b32_e32 v90, 1.0
	v_mov_b32_e32 v91, 1.0
	v_mov_b32_e32 v92, 1.0
	v_mov_b32_e32 v93, 1.0
	v_mov_b32_e32 v94, 1.0
	v_mov_b32_e32 v95, 1.0
	v_mov_b32_e32 v96, 1.0
	v_mov_b32_e32 v97, 1.0
.Lks2_inp:
	s_and_saveexec_b64 s[20:21], s[6:7]
	global_load_dword v0, v[10:11], off
	s_mov_b64 s[98:99], 0x5c60
	v_lshl_add_u64 v[88:89], v[10:11], 0, s[98:99]
	global_load_dword v1, v[88:89], off
	s_mov_b64 s[98:99], 0xb8c0
	v_lshl_add_u64 v[88:89], v[10:11], 0, s[98:99]
	global_load_dword v2, v[88:89], off
	s_mov_b64 s[98:99], 0x11520
	v_lshl_add_u64 v[88:89], v[10:11], 0, s[98:99]
	global_load_dword v3, v[88:89], off
	s_mov_b64 s[98:99], 0x17180
	v_lshl_add_u64 v[88:89], v[10:11], 0, s[98:99]
	global_load_dword v4, v[88:89], off
	s_mov_b64 s[98:99], 0x1cde0
	v_lshl_add_u64 v[88:89], v[10:11], 0, s[98:99]
	global_load_dword v5, v[88:89], off
	s_mov_b64 s[98:99], 0x22a40
	v_lshl_add_u64 v[88:89], v[10:11], 0, s[98:99]
	global_load_dword v6, v[88:89], off
	s_mov_b64 s[98:99], 0x286a0
	v_lshl_add_u64 v[88:89], v[10:11], 0, s[98:99]
	global_load_dword v7, v[88:89], off

; #define LAS __attribute__((address_space(3)))
; __device__ __forceinline__ unsigned pk2(float lo, float hi) { f32x2_t v = {lo, hi}; bf16x2_t b = __builtin_convertvector(v, bf16x2_t); return __builtin_bit_cast(unsigned, b); }
; template <int MAP> __device__ __forceinline__ void prep_w(const float* __restrict__ W, int K, int ldw, bf16_t* __restrict__ Bt, int Np, int ldb, LAS unsigned char* lds, int tid, int bx, int G, const float* kscale = nullptr) {
;     ...
;     for (; tile < ntiles; tile += G) {
;         const int tk = tile / ntp, tp = tile - tk * ntp;
;         u32x4 pw; pw.x = pk2(v[0], v[1]); pw.y = pk2(v[2], v[3]); pw.z = pk2(v[4], v[5]); pw.w = pk2(v[6], v[7]);
;         *(LAS u32x4*)(lds + lane * 144 + w * 16) = pw;
;         __syncthreads();
;         const int nx = tile + G;
;         if (nx < ntiles) { const int tk2 = nx / ntp, tp2 = nx - tk2 * ntp; const int col = mapcol<MAP>(tp2 * 64 + lane); const float* s = W + (size_t)(tk2 * 64 + 8 * w) * ldw + (col < 0 ? 0 : col);
; #pragma unroll
;             for (int i = 0; i < 8; ++i) v[i] = col >= 0 ? s[(size_t)i * ldw] * (kscale ? kscale[tk2 * 64 + 8 * w + i] : 1.0f) : 0.f; }
;         { const int p = tid >> 3, pc = tid & 7; const u32x4 o = *(LAS const u32x4*)(lds + p * 144 + pc * 16);
;             *(u32x4*)(Bt + (size_t)(tp * 64 + p) * ldb + tk * 64 + pc * 8) = o; }
.LBB0_56:
	v_ashrrev_i32_e32 v17, 3, v32
	v_and_b32_e32 v8, 7, v32
	s_andn2_b64 vcc, exec, s[18:19]
	v_lshlrev_b32_e32 v9, 4, v22
	v_lshlrev_b32_e32 v16, 3, v22
	v_lshlrev_b32_e32 v19, 1, v33
	v_mad_u32_u24 v18, v33, s85, v165
	v_mul_lo_u32 v21, v17, s85
	v_lshlrev_b32_e32 v20, 4, v8
	v_lshlrev_b32_e32 v8, 3, v8
	s_cbranch_vccnz .LBB0_112
	s_add_u32 s18, s8, 0x100000
	s_addc_u32 s19, s9, 0
	s_cmp_lg_u64 s[14:15], 0
	s_cselect_b64 s[20:21], -1, 0
	v_add_u32_e32 v10, 0x100, v21
	s_lshl_b32 s29, s27, 6
	s_add_i32 s4, s26, s27
	s_lshl_b32 s31, s26, 6
	v_or_b32_e32 v24, s29, v33
	v_lshl_or_b32 v25, s4, 7, v19
	s_lshl_b32 s30, s27, 7
	v_add_u32_e32 v26, v18, v9
	v_add_u32_e32 v27, v10, v20
	v_lshlrev_b32_e32 v10, 1, v8
	s_mov_b32 s35, s26
	s_branch .LBB0_62
.LBB0_60:
	s_or_b64 exec, exec, s[24:25]

; #define LAS __attribute__((address_space(3)))
; __device__ __forceinline__ unsigned pk2(float lo, float hi) { f32x2_t v = {lo, hi}; bf16x2_t b = __builtin_convertvector(v, bf16x2_t); return __builtin_bit_cast(unsigned, b); }
; template <int MAP> __device__ __forceinline__ void prep_w(const float* __restrict__ W, int K, int ldw, bf16_t* __restrict__ Bt, int Np, int ldb, LAS unsigned char* lds, int tid, int bx, int G, const float* kscale = nullptr) {
;     ...
;     for (; tile < ntiles; tile += G) {
;         const int tk = tile / ntp, tp = tile - tk * ntp;
;         u32x4 pw; pw.x = pk2(v[0], v[1]); pw.y = pk2(v[2], v[3]); pw.z = pk2(v[4], v[5]); pw.w = pk2(v[6], v[7]);
;         *(LAS u32x4*)(lds + lane * 144 + w * 16) = pw;
;         __syncthreads();
.LBB0_62:
	s_waitcnt vmcnt(0)
	v_mul_f32_e32 v0, v0, v90
	v_mul_f32_e32 v1, v1, v91
	v_mul_f32_e32 v2, v2, v92
	v_mul_f32_e32 v3, v3, v93
	v_mul_f32_e32 v4, v4, v94
	v_mul_f32_e32 v5, v5, v95
	v_mul_f32_e32 v6, v6, v96
	v_mul_f32_e32 v7, v7, v97
	s_add_i32 s34, s35, s27
	s_cmpk_gt_i32 s34, 0x5ff
	v_cvt_pk_bf16_f32 v12, v0, v1
	v_cvt_pk_bf16_f32 v13, v2, v3
	v_cvt_pk_bf16_f32 v14, v4, v5
	v_cvt_pk_bf16_f32 v15, v6, v7
	s_cselect_b64 s[22:23], -1, 0
	s_cmpk_lt_i32 s34, 0x600
	s_mov_b64 s[4:5], -1
	ds_write_b128 v26, v[12:15]
	s_waitcnt lgkmcnt(0)
	s_barrier
	s_cbranch_scc1 .LBB0_64
	s_add_i32 s36, s31, s29
	s_mov_b64 s[4:5], 0

; template <int MAP> __device__ __forceinline__ void prep_w(const float* __restrict__ W, int K, int ldw, bf16_t* __restrict__ Bt, int Np, int ldb, LAS unsigned char* lds, int tid, int bx, int G, const float* kscale = nullptr) {
;     ...
;         const int nx = tile + G;
;         if (nx < ntiles) { const int tk2 = nx / ntp, tp2 = nx - tk2 * ntp; const int col = mapcol<MAP>(tp2 * 64 + lane); const float* s = W + (size_t)(tk2 * 64 + 8 * w) * ldw + (col < 0 ? 0 : col);
; #pragma unroll
;             for (int i = 0; i < 8; ++i) v[i] = col >= 0 ? s[(size_t)i * ldw] * (kscale ? kscale[tk2 * 64 + 8 * w + i] : 1.0f) : 0.f; }
.LBB0_73:
	v_lshl_add_u32 v12, s6, 6, v16
	v_mov_b64_e32 v[2:3], s[16:17]
	v_mad_i64_i32 v[2:3], s[4:5], v12, s61, v[2:3]
	v_max_i32_e32 v80, 0, v1
	v_cmp_lt_i32_e64 s[6:7], -1, v1
	v_cndmask_b32_e64 v1, 0, 1, s[20:21]
	v_ashrrev_i32_e32 v13, 31, v12
	v_lshl_add_u64 v[14:15], v[80:81], 2, v[2:3]
	v_mov_b32_e32 v0, 0
	v_cmp_ne_u32_e64 s[4:5], 1, v1
	v_mov_b32_e32 v1, 0
	v_mov_b32_e32 v2, 0
	v_mov_b32_e32 v3, 0
	v_mov_b32_e32 v4, 0
	v_mov_b32_e32 v5, 0
	v_mov_b32_e32 v6, 0
	v_mov_b32_e32 v7, 0
	s_and_b64 vcc, exec, s[4:5]
	s_cbranch_vccnz .Lks1_inl
	v_lshl_add_u64 v[88:89], v[12:13], 2, s[14:15]
	global_load_dwordx4 v[90:93], v[88:89], off
	global_load_dwordx4 v[94:97], v[88:89], off offset:16
	s_branch .Lks2_inl

; template <int MAP> __device__ __forceinline__ void prep_w(const float* __restrict__ W, int K, int ldw, bf16_t* __restrict__ Bt, int Np, int ldb, LAS unsigned char* lds, int tid, int bx, int G, const float* kscale = nullptr) {
;     ...
;         if (nx < ntiles) { const int tk2 = nx / ntp, tp2 = nx - tk2 * ntp; const int col = mapcol<MAP>(tp2 * 64 + lane); const float* s = W + (size_t)(tk2 * 64 + 8 * w) * ldw + (col < 0 ? 0 : col);
; #pragma unroll
;             for (int i = 0; i < 8; ++i) v[i] = col >= 0 ? s[(size_t)i * ldw] * (kscale ? kscale[tk2 * 64 + 8 * w + i] : 1.0f) : 0.f; }
.Lks2_inl:
	s_and_saveexec_b64 s[24:25], s[6:7]
	global_load_dword v0, v[14:15], off
	s_mov_b64 s[98:99], 0x5c60
	v_lshl_add_u64 v[88:89], v[14:15], 0, s[98:99]
	global_load_dword v1, v[88:89], off
	s_mov_b64 s[98:99], 0xb8c0
	v_lshl_add_u64 v[88:89], v[14:15], 0, s[98:99]
	global_load_dword v2, v[88:89], off
	s_mov_b64 s[98:99], 0x11520
	v_lshl_add_u64 v[88:89], v[14:15], 0, s[98:99]
	global_load_dword v3, v[88:89], off
	s_mov_b64 s[98:99], 0x17180
	v_lshl_add_u64 v[88:89], v[14:15], 0, s[98:99]
	global_load_dword v4, v[88:89], off
	s_mov_b64 s[98:99], 0x1cde0
	v_lshl_add_u64 v[88:89], v[14:15], 0, s[98:99]
	global_load_dword v5, v[88:89], off
	s_mov_b64 s[98:99], 0x22a40
	v_lshl_add_u64 v[88:89], v[14:15], 0, s[98:99]
	global_load_dword v6, v[88:89], off
	s_mov_b64 s[98:99], 0x286a0
	v_lshl_add_u64 v[88:89], v[14:15], 0, s[98:99]
	global_load_dword v7, v[88:89], off
	s_branch .LBB0_60

; #define LAS __attribute__((address_space(3)))
; template <int MAP> __device__ __forceinline__ int mapcol(int p) {
;     const int pn = p >> 8, q = p & 255, bj = q >> 7, wc = (q >> 5) & 3, n = (q >> 4) & 1, fq = (q >> 2) & 3, e = q & 3;
;     const int lc = 64 * wc + 32 * bj + 8 * fq + 4 * n + e;
;     if (MAP == 3) return p;
;     if (MAP == 0) return 256 * pn + lc;
;     if (MAP == 1) { if (pn <= 10) return 256 * pn + lc; if (pn == 11) return lc < 24 ? 2816 + lc : -1; return 2840 + 256 * (pn - 12) + lc; }
;     const int j = 128 * pn + 32 * wc + 8 * fq + 4 * n + e; return bj ? DFF + j : j;
; template <int MAP> __device__ __forceinline__ void prep_w(const float* __restrict__ W, int K, int ldw, bf16_t* __restrict__ Bt, int Np, int ldb, LAS unsigned char* lds, int tid, int bx, int G, const float* kscale = nullptr) {
;     const int ntp = Np >> 6, ntiles = ntp * (K >> 6), w = tid >> 6, lane = tid & 63;
;     float v[8];
;     int tile = bx;
;     if (tile < ntiles) { const int tk = tile / ntp, tp = tile - tk * ntp; const int col = mapcol<MAP>(tp * 64 + lane); const float* s = W + (size_t)(tk * 64 + 8 * w) * ldw + (col < 0 ? 0 : col);
; #pragma unroll
;         for (int i = 0; i < 8; ++i) v[i] = col >= 0 ? s[(size_t)i * ldw] * (kscale ? kscale[tk * 64 + 8 * w + i] : 1.0f) : 0.f; }
.LBB0_186:
	s_mov_b32 s4, 14
	s_ashr_i32 s5, s4, 31
	s_lshl_b64 s[4:5], s[4:5], 3
	s_add_u32 s4, s0, s4
	s_addc_u32 s5, s1, s5
	s_load_dwordx2 s[4:5], s[4:5], 0x0
	s_mul_i32 s14, s10, 0x1600000
	s_mul_hi_i32 s7, s10, 0x1600000
	s_mov_b32 s6, 13
	s_waitcnt lgkmcnt(0)
	s_add_u32 s14, s4, s14
	s_addc_u32 s15, s5, s7
	s_ashr_i32 s7, s6, 31
	s_lshl_b64 s[4:5], s[6:7], 3
	s_add_u32 s4, s0, s4
	s_addc_u32 s5, s1, s5
	s_load_dwordx2 s[20:21], s[4:5], 0x0
	s_lshl_b32 s4, s10, 10
	s_ashr_i32 s5, s4, 31
	s_lshl_b64 s[4:5], s[4:5], 2
	s_waitcnt vmcnt(1)
	v_lshrrev_b32_e32 v0, 2, v32
	s_waitcnt lgkmcnt(0)
	s_add_u32 s16, s20, s4
	s_addc_u32 s17, s21, s5
	s_cmpk_lt_i32 s26, 0x580
	s_cselect_b64 s[18:19], -1, 0
	s_cmpk_gt_i32 s26, 0x57f
	v_and_b32_e32 v14, 4, v0
	s_cbranch_scc1 .LBB0_195
	s_mul_hi_i32 s4, s26, 0x2e8ba2e9
	s_lshr_b32 s5, s4, 31
	s_ashr_i32 s4, s4, 4
	s_add_i32 s4, s4, s5
	s_mul_i32 s5, s4, 0xffffffa8
	s_add_i32 s5, s5, s26
	s_lshl_b32 s6, s5, 6
	s_lshl_b32 s5, s5, 5
	v_mov_b32_e32 v0, 0x63
	s_and_b32 s5, s5, 0xffffff80
	v_bitop3_b32 v0, s6, v0, v33 bitop3:0xc8
	v_and_or_b32 v1, v19, 24, v14
	v_or3_b32 v0, v1, s5, v0
	s_bitcmp0_b32 s26, 1
	v_add_u32_e32 v1, 0xb00, v0
	s_cselect_b64 vcc, -1, 0
	s_lshl_b32 s4, s4, 6
	v_cndmask_b32_e32 v2, v1, v0, vcc
	v_lshl_add_u32 v10, v22, 3, s4
	v_mov_b64_e32 v[0:1], s[14:15]
	v_mad_i64_i32 v[0:1], s[4:5], v10, s63, v[0:1]
	s_cmp_lg_u64 s[20:21], 0
	v_max_i32_e32 v80, 0, v2
	s_cselect_b64 s[4:5], -1, 0
	v_lshl_add_u64 v[12:13], v[80:81], 2, v[0:1]
	v_cndmask_b32_e64 v1, 0, 1, s[4:5]
	v_ashrrev_i32_e32 v11, 31, v10
	v_cmp_lt_i32_e64 s[6:7], -1, v2
	v_mov_b32_e32 v0, 0
	v_cmp_ne_u32_e64 s[4:5], 1, v1
	v_mov_b32_e32 v1, 0
	v_mov_b32_e32 v2, 0
	v_mov_b32_e32 v3, 0
	v_mov_b32_e32 v4, 0
	v_mov_b32_e32 v5, 0
	v_mov_b32_e32 v6, 0
	v_mov_b32_e32 v7, 0
	s_and_b64 vcc, exec, s[4:5]
	s_cbranch_vccnz .Lks1_gup
	v_lshl_add_u64 v[88:89], v[10:11], 2, s[16:17]
	global_load_dwordx4 v[90:93], v[88:89], off
	global_load_dwordx4 v[94:97], v[88:89], off offset:16
	s_branch .Lks2_gup

; template <int MAP> __device__ __forceinline__ void prep_w(const float* __restrict__ W, int K, int ldw, bf16_t* __restrict__ Bt, int Np, int ldb, LAS unsigned char* lds, int tid, int bx, int G, const float* kscale = nullptr) {
;     ...
;     if (tile < ntiles) { const int tk = tile / ntp, tp = tile - tk * ntp; const int col = mapcol<MAP>(tp * 64 + lane); const float* s = W + (size_t)(tk * 64 + 8 * w) * ldw + (col < 0 ? 0 : col);
; #pragma unroll
;         for (int i = 0; i < 8; ++i) v[i] = col >= 0 ? s[(size_t)i * ldw] * (kscale ? kscale[tk * 64 + 8 * w + i] : 1.0f) : 0.f; }
;     for (; tile < ntiles; tile += G) {
.Lks2_gup:
	s_and_saveexec_b64 s[22:23], s[6:7]
	global_load_dword v0, v[12:13], off
	s_mov_b64 s[98:99], 0x5800
	v_lshl_add_u64 v[88:89], v[12:13], 0, s[98:99]
	global_load_dword v1, v[88:89], off
	s_mov_b64 s[98:99], 0xb000
	v_lshl_add_u64 v[88:89], v[12:13], 0, s[98:99]
	global_load_dword v2, v[88:89], off
	s_mov_b64 s[98:99], 0x10800
	v_lshl_add_u64 v[88:89], v[12:13], 0, s[98:99]
	global_load_dword v3, v[88:89], off
	s_mov_b64 s[98:99], 0x16000
	v_lshl_add_u64 v[88:89], v[12:13], 0, s[98:99]
	global_load_dword v4, v[88:89], off
	s_mov_b64 s[98:99], 0x1b800
	v_lshl_add_u64 v[88:89], v[12:13], 0, s[98:99]
	global_load_dword v5, v[88:89], off
	s_mov_b64 s[98:99], 0x21000
	v_lshl_add_u64 v[88:89], v[12:13], 0, s[98:99]
	global_load_dword v6, v[88:89], off
	s_mov_b64 s[98:99], 0x26800
	v_lshl_add_u64 v[88:89], v[12:13], 0, s[98:99]
	global_load_dword v7, v[88:89], off
	s_branch .LBB0_228
.LBB0_195:
	v_mov_b32_e32 v80, v81
	v_mov_b32_e32 v82, v81
	v_mov_b32_e32 v83, v81
	v_mov_b32_e32 v84, v81
	v_mov_b32_e32 v85, v81
	v_mov_b32_e32 v86, v81
	v_mov_b32_e32 v87, v81
	v_mov_b64_e32 v[0:1], v[80:81]
	v_mov_b64_e32 v[2:3], v[82:83]
	v_mov_b64_e32 v[4:5], v[84:85]
	v_mov_b64_e32 v[6:7], v[86:87]
	s_andn2_b64 vcc, exec, s[18:19]
	s_cbranch_vccz .LBB0_229
	s_branch .LBB0_274
.LBB0_228:
	s_or_b64 exec, exec, s[22:23]
	s_andn2_b64 vcc, exec, s[18:19]
	s_cbranch_vccnz .LBB0_274
.LBB0_229:
	s_add_u32 s18, s8, 0x1100000
	s_addc_u32 s19, s9, 0
	s_cmp_lg_u64 s[20:21], 0
	s_cselect_b64 s[20:21], -1, 0
	v_add_u32_e32 v10, 0x100, v21
	s_add_i32 s4, s26, s27
	s_lshl_b32 s31, s27, 6
	v_and_or_b32 v22, v19, 24, v14
	s_lshl_b32 s29, s4, 5
	s_lshl_b32 s30, s27, 5
	v_or_b32_e32 v23, s31, v33
	s_lshl_b32 s34, s26, 6
	v_add_u32_e32 v24, v18, v9
	v_add_u32_e32 v25, v10, v20
	v_lshlrev_b32_e32 v10, 1, v8
	s_mov_b32 s36, s26
	s_branch .LBB0_234
.LBB0_232:
	s_or_b64 exec, exec, s[24:25]

; #define LAS __attribute__((address_space(3)))
; __device__ __forceinline__ unsigned pk2(float lo, float hi) { f32x2_t v = {lo, hi}; bf16x2_t b = __builtin_convertvector(v, bf16x2_t); return __builtin_bit_cast(unsigned, b); }
; template <int MAP> __device__ __forceinline__ int mapcol(int p) {
;     const int pn = p >> 8, q = p & 255, bj = q >> 7, wc = (q >> 5) & 3, n = (q >> 4) & 1, fq = (q >> 2) & 3, e = q & 3;
;     const int lc = 64 * wc + 32 * bj + 8 * fq + 4 * n + e;
;     if (MAP == 3) return p;
;     if (MAP == 0) return 256 * pn + lc;
;     if (MAP == 1) { if (pn <= 10) return 256 * pn + lc; if (pn == 11) return lc < 24 ? 2816 + lc : -1; return 2840 + 256 * (pn - 12) + lc; }
;     const int j = 128 * pn + 32 * wc + 8 * fq + 4 * n + e; return bj ? DFF + j : j;
; template <int MAP> __device__ __forceinline__ void prep_w(const float* __restrict__ W, int K, int ldw, bf16_t* __restrict__ Bt, int Np, int ldb, LAS unsigned char* lds, int tid, int bx, int G, const float* kscale = nullptr) {
;     ...
;         u32x4 pw; pw.x = pk2(v[0], v[1]); pw.y = pk2(v[2], v[3]); pw.z = pk2(v[4], v[5]); pw.w = pk2(v[6], v[7]);
;         *(LAS u32x4*)(lds + lane * 144 + w * 16) = pw;
;         __syncthreads();
;         const int nx = tile + G;
;         if (nx < ntiles) { const int tk2 = nx / ntp, tp2 = nx - tk2 * ntp; const int col = mapcol<MAP>(tp2 * 64 + lane); const float* s = W + (size_t)(tk2 * 64 + 8 * w) * ldw + (col < 0 ? 0 : col);
; #pragma unroll
;             for (int i = 0; i < 8; ++i) v[i] = col >= 0 ? s[(size_t)i * ldw] * (kscale ? kscale[tk2 * 64 + 8 * w + i] : 1.0f) : 0.f; }
.LBB0_234:
	s_waitcnt vmcnt(0)
	v_mul_f32_e32 v0, v0, v90
	v_mul_f32_e32 v1, v1, v91
	v_mul_f32_e32 v2, v2, v92
	v_mul_f32_e32 v3, v3, v93
	v_mul_f32_e32 v4, v4, v94
	v_mul_f32_e32 v5, v5, v95
	v_mul_f32_e32 v6, v6, v96
	v_mul_f32_e32 v7, v7, v97
	s_add_i32 s35, s36, s27
	s_cmpk_gt_i32 s35, 0x57f
	s_cselect_b64 s[22:23], -1, 0
	v_cvt_pk_bf16_f32 v12, v0, v1
	v_cvt_pk_bf16_f32 v13, v2, v3
	v_cvt_pk_bf16_f32 v14, v4, v5
	v_cvt_pk_bf16_f32 v15, v6, v7
	s_and_b64 vcc, exec, s[22:23]
	ds_write_b128 v24, v[12:15]
	s_waitcnt lgkmcnt(0)
	s_barrier
	s_cbranch_vccnz .LBB0_233
	s_mul_hi_i32 s4, s35, 0x2e8ba2e9
	s_lshr_b32 s5, s4, 31
	s_ashr_i32 s4, s4, 4
	s_add_i32 s4, s4, s5
	s_mul_i32 s5, s4, 0xfffff500
	v_add_u32_e32 v0, s34, v23
	s_add_i32 s5, s29, s5
	s_and_b32 s5, s5, 0xffffff80
	v_and_b32_e32 v0, 0x63, v0
	v_or3_b32 v0, v22, s5, v0
	s_bitcmp0_b32 s35, 1
	v_add_u32_e32 v1, 0xb00, v0
	s_cselect_b64 vcc, -1, 0
	v_cndmask_b32_e32 v2, v1, v0, vcc
	v_lshl_add_u32 v12, s4, 6, v16
	v_mov_b64_e32 v[0:1], s[14:15]
	v_mad_i64_i32 v[0:1], s[4:5], v12, s63, v[0:1]
	v_max_i32_e32 v80, 0, v2
	v_lshl_add_u64 v[14:15], v[80:81], 2, v[0:1]
	v_cndmask_b32_e64 v1, 0, 1, s[20:21]
	v_ashrrev_i32_e32 v13, 31, v12
	v_cmp_lt_i32_e64 s[6:7], -1, v2
	v_mov_b32_e32 v0, 0
	v_cmp_ne_u32_e64 s[4:5], 1, v1
	v_mov_b32_e32 v1, 0
	v_mov_b32_e32 v2, 0
	v_mov_b32_e32 v3, 0
	v_mov_b32_e32 v4, 0
	v_mov_b32_e32 v5, 0
	v_mov_b32_e32 v6, 0
	v_mov_b32_e32 v7, 0
	s_and_b64 vcc, exec, s[4:5]
	s_cbranch_vccnz .Lks1_gul
	v_lshl_add_u64 v[88:89], v[12:13], 2, s[16:17]
	global_load_dwordx4 v[90:93], v[88:89], off
	global_load_dwordx4 v[94:97], v[88:89], off offset:16
	s_branch .Lks2_gul

; template <int MAP> __device__ __forceinline__ void prep_w(const float* __restrict__ W, int K, int ldw, bf16_t* __restrict__ Bt, int Np, int ldb, LAS unsigned char* lds, int tid, int bx, int G, const float* kscale = nullptr) {
;     ...
;         if (nx < ntiles) { const int tk2 = nx / ntp, tp2 = nx - tk2 * ntp; const int col = mapcol<MAP>(tp2 * 64 + lane); const float* s = W + (size_t)(tk2 * 64 + 8 * w) * ldw + (col < 0 ? 0 : col);
; #pragma unroll
;             for (int i = 0; i < 8; ++i) v[i] = col >= 0 ? s[(size_t)i * ldw] * (kscale ? kscale[tk2 * 64 + 8 * w + i] : 1.0f) : 0.f; }
.Lks2_gul:
	s_and_saveexec_b64 s[24:25], s[6:7]
	global_load_dword v0, v[14:15], off
	s_mov_b64 s[98:99], 0x5800
	v_lshl_add_u64 v[88:89], v[14:15], 0, s[98:99]
	global_load_dword v1, v[88:89], off
	s_mov_b64 s[98:99], 0xb000
	v_lshl_add_u64 v[88:89], v[14:15], 0, s[98:99]
	global_load_dword v2, v[88:89], off
	s_mov_b64 s[98:99], 0x10800
	v_lshl_add_u64 v[88:89], v[14:15], 0, s[98:99]
	global_load_dword v3, v[88:89], off
	s_mov_b64 s[98:99], 0x16000
	v_lshl_add_u64 v[88:89], v[14:15], 0, s[98:99]
	global_load_dword v4, v[88:89], off
	s_mov_b64 s[98:99], 0x1b800
	v_lshl_add_u64 v[88:89], v[14:15], 0, s[98:99]
	global_load_dword v5, v[88:89], off
	s_mov_b64 s[98:99], 0x21000
	v_lshl_add_u64 v[88:89], v[14:15], 0, s[98:99]
	global_load_dword v6, v[88:89], off
	s_mov_b64 s[98:99], 0x26800
	v_lshl_add_u64 v[88:89], v[14:15], 0, s[98:99]
	global_load_dword v7, v[88:89], off
	s_branch .LBB0_232
